# same as previous version; carry-out SGPR pair of the in-loop address multiply-add separated from the pair written right after it
# speedup vs baseline: 1.0087x; 1.0033x over previous
; #define PG8_STAGE(bufoff, gbase, voff) do { _Pragma("unroll") for (int _i = 0; _i < 2; ++_i) \
;         __builtin_amdgcn_global_load_lds((const unsigned*)((const char*)(gbase) + (voff)[_i]), (LAS unsigned*)(lds + (bufoff) + ldsw + _i * 8192), 16, 0, 0); } while (0)
; #define PG8_LDA(dst, b, h) do { _Pragma("unroll") for (int m = 0; m < 4; ++m) _Pragma("unroll") for (int k = 0; k < 2; ++k) dst[m][k] = *(const LAS bf16x8*)(lds + PG8_SA(b, h) + aoff + m * 2048 + k * 1024); } while (0)
; #define PG8_LDB(dst, b, h) do { _Pragma("unroll") for (int n = 0; n < 2; ++n) _Pragma("unroll") for (int k = 0; k < 2; ++k) dst[n][k] = *(const LAS bf16x8*)(lds + PG8_SB(b, h) + boff + n * 2048 + k * 1024); } while (0)
; #define PG8_MMA(ai, bj, At, Bt) do { __builtin_amdgcn_s_setprio(1); _Pragma("unroll") for (int m = 0; m < 4; ++m) _Pragma("unroll") for (int n = 0; n < 2; ++n) _Pragma("unroll") for (int k = 0; k < 2; ++k) \
;         acc[ai][bj][m][n] = __builtin_amdgcn_mfma_f32_16x16x32_bf16(Bt[n][k], At[m][k], acc[ai][bj][m][n], 0, 0, 0); __builtin_amdgcn_s_setprio(0); } while (0)
; #define PG8_WAIT_V(n) asm volatile("s_waitcnt vmcnt(" #n ")" ::: "memory")
; #define PG8_WAIT_L(n) asm volatile("s_waitcnt lgkmcnt(" #n ")" ::: "memory")
; #define PG8_BAR __builtin_amdgcn_s_barrier()
; #define PG8_SCHED __builtin_amdgcn_sched_barrier(0)
; template <class Epi>
; __device__ __forceinline__ void gemm_phase(LAS unsigned char* lds, const Gemm g, const StaticOrder& S, const Epi& E) {
;     ...
;             PG8_LDB(B0, 0, 0); PG8_SCHED; PG8_LDA(At, 0, 0); PG8_STAGE(PG8_SA(1, 1), a1 + hstepA, voffA);
;             PG8_WAIT_L(8); PG8_BAR; PG8_WAIT_L(0); PG8_MMA(0, 0, At, B0); PG8_BAR; PG8_SCHED;
;             PG8_LDB(B1, 0, 1); PG8_STAGE(PG8_SB(0, 0), b2, voffB);
;             PG8_BAR; PG8_WAIT_L(0); PG8_MMA(0, 1, At, B1); PG8_BAR;
;             PG8_LDA(At, 0, 1); PG8_STAGE(PG8_SA(0, 0), a2, voffA);
;             PG8_BAR; PG8_WAIT_L(0); PG8_MMA(1, 0, At, B0); PG8_BAR; PG8_SCHED;
;             PG8_STAGE(PG8_SB(0, 1), b2 + hstepB, voffB);
;             PG8_WAIT_V(6); PG8_BAR; PG8_MMA(1, 1, At, B1); PG8_BAR;
;             PG8_LDB(B0, 1, 0); PG8_SCHED; PG8_LDA(At, 1, 0); PG8_STAGE(PG8_SA(0, 1), a2 + hstepA, voffA);
;             PG8_WAIT_L(8); PG8_BAR; PG8_WAIT_L(0); PG8_MMA(0, 0, At, B0); PG8_BAR; PG8_SCHED;
.LBB0_116:
	s_add_i32 s35, s44, 2
	s_add_u32 s46, s36, 0x80
	s_addc_u32 s45, s37, 0
	s_cmp_eq_u32 s17, s44
	s_cselect_b32 s45, s29, s45
	s_cselect_b32 s44, s28, s46
	s_cselect_b32 s47, s31, s70
	s_cselect_b32 s46, s30, s69
	v_lshl_add_u64 v[166:167], s[36:37], 0, v[186:187]
	s_add_i32 m0, s39, 0xc000
	ds_read_b128 v[146:149], v228
	ds_read_b128 v[150:153], v228 offset:1024
	ds_read_b128 v[154:157], v228 offset:2048
	ds_read_b128 v[158:161], v228 offset:3072
	ds_read_b128 v[162:165], v228 offset:4096
	ds_read_b128 v[190:193], v228 offset:5120
	ds_read_b128 v[194:197], v228 offset:6144
	ds_read_b128 v[198:201], v228 offset:7168
	global_load_lds_dwordx4 v[166:167], off
	v_lshl_add_u64 v[166:167], s[36:37], 0, v[188:189]
	s_add_i32 m0, s39, 0xe000
	v_add_u32_e32 v142, 0x10000, v225
	global_load_lds_dwordx4 v[166:167], off
	ds_read_b128 v[130:133], v142
	ds_read_b128 v[134:137], v142 offset:1024
	ds_read_b128 v[138:141], v142 offset:2048
	ds_read_b128 v[142:145], v142 offset:3072
	v_add_u32_e32 v166, 0x14000, v225
	ds_read_b128 v[202:205], v166
	ds_read_b128 v[230:233], v166 offset:1024
	ds_read_b128 v[234:237], v166 offset:2048
	ds_read_b128 v[238:241], v166 offset:3072
	s_waitcnt vmcnt(8) lgkmcnt(0)
	s_barrier
	v_mfma_f32_16x16x32_bf16 v[124:127], v[130:133], v[146:149], v[124:127]
	v_mfma_f32_16x16x32_bf16 v[120:123], v[138:141], v[146:149], v[120:123]
	v_mfma_f32_16x16x32_bf16 v[112:115], v[130:133], v[154:157], v[112:115]
	v_mfma_f32_16x16x32_bf16 v[104:107], v[138:141], v[154:157], v[104:107]
	v_mfma_f32_16x16x32_bf16 v[96:99], v[130:133], v[162:165], v[96:99]
	v_mfma_f32_16x16x32_bf16 v[88:91], v[138:141], v[162:165], v[88:91]
	v_mfma_f32_16x16x32_bf16 v[80:83], v[130:133], v[194:197], v[80:83]
	v_mfma_f32_16x16x32_bf16 v[72:75], v[138:141], v[194:197], v[72:75]
	v_mfma_f32_16x16x32_bf16 v[124:127], v[134:137], v[150:153], v[124:127]
	v_mfma_f32_16x16x32_bf16 v[120:123], v[142:145], v[150:153], v[120:123]
	v_mfma_f32_16x16x32_bf16 v[112:115], v[134:137], v[158:161], v[112:115]
	v_mfma_f32_16x16x32_bf16 v[104:107], v[142:145], v[158:161], v[104:107]
	v_mfma_f32_16x16x32_bf16 v[96:99], v[134:137], v[190:193], v[96:99]
	v_mfma_f32_16x16x32_bf16 v[88:91], v[142:145], v[190:193], v[88:91]
	v_mfma_f32_16x16x32_bf16 v[80:83], v[134:137], v[198:201], v[80:83]
	v_mfma_f32_16x16x32_bf16 v[72:75], v[142:145], v[198:201], v[72:75]
	v_mfma_f32_16x16x32_bf16 v[116:119], v[202:205], v[146:149], v[116:119]
	v_mfma_f32_16x16x32_bf16 v[108:111], v[234:237], v[146:149], v[108:111]
	v_mfma_f32_16x16x32_bf16 v[100:103], v[202:205], v[154:157], v[100:103]
	v_mfma_f32_16x16x32_bf16 v[92:95], v[234:237], v[154:157], v[92:95]
	v_mfma_f32_16x16x32_bf16 v[84:87], v[202:205], v[162:165], v[84:87]
	v_mfma_f32_16x16x32_bf16 v[76:79], v[234:237], v[162:165], v[76:79]
	v_mfma_f32_16x16x32_bf16 v[68:71], v[202:205], v[194:197], v[68:71]
	v_mfma_f32_16x16x32_bf16 v[64:67], v[234:237], v[194:197], v[64:67]
	v_mfma_f32_16x16x32_bf16 v[116:119], v[230:233], v[150:153], v[116:119]
	v_mfma_f32_16x16x32_bf16 v[108:111], v[238:241], v[150:153], v[108:111]
	v_mfma_f32_16x16x32_bf16 v[100:103], v[230:233], v[158:161], v[100:103]
	v_mfma_f32_16x16x32_bf16 v[92:95], v[238:241], v[158:161], v[92:95]
	v_mfma_f32_16x16x32_bf16 v[84:87], v[230:233], v[190:193], v[84:87]
	v_mfma_f32_16x16x32_bf16 v[76:79], v[238:241], v[190:193], v[76:79]
	v_mfma_f32_16x16x32_bf16 v[68:71], v[230:233], v[198:201], v[68:71]
	v_mfma_f32_16x16x32_bf16 v[64:67], v[238:241], v[198:201], v[64:67]
	s_barrier
	ds_read_b128 v[146:149], v228 offset:16384
	ds_read_b128 v[150:153], v228 offset:17408
	ds_read_b128 v[154:157], v228 offset:18432
	ds_read_b128 v[158:161], v228 offset:19456
	ds_read_b128 v[162:165], v228 offset:20480
	ds_read_b128 v[190:193], v228 offset:21504
	ds_read_b128 v[194:197], v228 offset:22528
	ds_read_b128 v[198:201], v228 offset:23552
	s_add_i32 s71, s57, 0x10000
	v_lshl_add_u64 v[166:167], s[46:47], 0, v[168:169]
	s_mov_b32 m0, s71
	v_lshl_add_u64 v[206:207], s[46:47], 0, v[178:179]
	global_load_lds_dwordx4 v[166:167], off
	s_add_i32 m0, s71, 0x2000
	v_lshl_add_u64 v[242:243], s[44:45], 0, v[174:175]
	global_load_lds_dwordx4 v[206:207], off
	s_mov_b32 m0, s39
	v_lshl_add_u64 v[244:245], s[44:45], 0, v[176:177]
	global_load_lds_dwordx4 v[242:243], off
	s_mov_b32 m0, s54
	s_add_u32 s46, s46, s50
	s_addc_u32 s47, s47, 0
	global_load_lds_dwordx4 v[244:245], off
	s_add_i32 s71, s57, 0x14000
	v_lshl_add_u64 v[246:247], s[46:47], 0, v[168:169]
	s_mov_b32 m0, s71
	v_lshl_add_u64 v[248:249], s[46:47], 0, v[178:179]
	global_load_lds_dwordx4 v[246:247], off
	s_add_i32 m0, s71, 0x2000
	s_nop 0
	global_load_lds_dwordx4 v[248:249], off
	s_waitcnt vmcnt(8) lgkmcnt(0)
	s_barrier
; #define PG8_STAGE(bufoff, gbase, voff) do { _Pragma("unroll") for (int _i = 0; _i < 2; ++_i) \
;         __builtin_amdgcn_global_load_lds((const unsigned*)((const char*)(gbase) + (voff)[_i]), (LAS unsigned*)(lds + (bufoff) + ldsw + _i * 8192), 16, 0, 0); } while (0)
; #define PG8_LDA(dst, b, h) do { _Pragma("unroll") for (int m = 0; m < 4; ++m) _Pragma("unroll") for (int k = 0; k < 2; ++k) dst[m][k] = *(const LAS bf16x8*)(lds + PG8_SA(b, h) + aoff + m * 2048 + k * 1024); } while (0)
; #define PG8_LDB(dst, b, h) do { _Pragma("unroll") for (int n = 0; n < 2; ++n) _Pragma("unroll") for (int k = 0; k < 2; ++k) dst[n][k] = *(const LAS bf16x8*)(lds + PG8_SB(b, h) + boff + n * 2048 + k * 1024); } while (0)
; #define PG8_MMA(ai, bj, At, Bt) do { __builtin_amdgcn_s_setprio(1); _Pragma("unroll") for (int m = 0; m < 4; ++m) _Pragma("unroll") for (int n = 0; n < 2; ++n) _Pragma("unroll") for (int k = 0; k < 2; ++k) \
;         acc[ai][bj][m][n] = __builtin_amdgcn_mfma_f32_16x16x32_bf16(Bt[n][k], At[m][k], acc[ai][bj][m][n], 0, 0, 0); __builtin_amdgcn_s_setprio(0); } while (0)
; #define PG8_WAIT_V(n) asm volatile("s_waitcnt vmcnt(" #n ")" ::: "memory")
; #define PG8_WAIT_L(n) asm volatile("s_waitcnt lgkmcnt(" #n ")" ::: "memory")
; #define PG8_BAR __builtin_amdgcn_s_barrier()
; #define PG8_SCHED __builtin_amdgcn_sched_barrier(0)
; template <class Epi>
; __device__ __forceinline__ void gemm_phase(LAS unsigned char* lds, const Gemm g, const StaticOrder& S, const Epi& E) {
;     ...
;             PG8_BAR; PG8_WAIT_L(0); PG8_MMA(1, 0, At, B0); PG8_BAR; PG8_SCHED;
;             PG8_STAGE(PG8_SB(0, 1), b2 + hstepB, voffB);
;             PG8_WAIT_V(6); PG8_BAR; PG8_MMA(1, 1, At, B1); PG8_BAR;
;             PG8_LDB(B0, 1, 0); PG8_SCHED; PG8_LDA(At, 1, 0); PG8_STAGE(PG8_SA(0, 1), a2 + hstepA, voffA);
;             PG8_WAIT_L(8); PG8_BAR; PG8_WAIT_L(0); PG8_MMA(0, 0, At, B0); PG8_BAR; PG8_SCHED;
;             PG8_LDB(B1, 1, 1); PG8_STAGE(PG8_SB(1, 0), b3, voffB);
;             PG8_BAR; PG8_WAIT_L(0); PG8_MMA(0, 1, At, B1); PG8_BAR;
;             PG8_LDA(At, 1, 1); PG8_STAGE(PG8_SA(1, 0), a3, voffA);
;             PG8_BAR; PG8_WAIT_L(0); PG8_MMA(1, 0, At, B0); PG8_BAR; PG8_SCHED;
	v_mfma_f32_16x16x32_bf16 v[60:63], v[130:133], v[146:149], v[60:63]
	v_mfma_f32_16x16x32_bf16 v[56:59], v[138:141], v[146:149], v[56:59]
	v_mfma_f32_16x16x32_bf16 v[52:55], v[130:133], v[154:157], v[52:55]
	v_mfma_f32_16x16x32_bf16 v[44:47], v[138:141], v[154:157], v[44:47]
	v_mfma_f32_16x16x32_bf16 v[36:39], v[130:133], v[162:165], v[36:39]
	v_mfma_f32_16x16x32_bf16 v[28:31], v[138:141], v[162:165], v[28:31]
	v_mfma_f32_16x16x32_bf16 v[20:23], v[130:133], v[194:197], v[20:23]
	v_mfma_f32_16x16x32_bf16 v[12:15], v[138:141], v[194:197], v[12:15]
	v_mfma_f32_16x16x32_bf16 v[60:63], v[134:137], v[150:153], v[60:63]
	v_mfma_f32_16x16x32_bf16 v[56:59], v[142:145], v[150:153], v[56:59]
	v_mfma_f32_16x16x32_bf16 v[52:55], v[134:137], v[158:161], v[52:55]
	v_mfma_f32_16x16x32_bf16 v[44:47], v[142:145], v[158:161], v[44:47]
	v_mfma_f32_16x16x32_bf16 v[36:39], v[134:137], v[190:193], v[36:39]
	v_mfma_f32_16x16x32_bf16 v[28:31], v[142:145], v[190:193], v[28:31]
	v_mfma_f32_16x16x32_bf16 v[20:23], v[134:137], v[198:201], v[20:23]
	v_mfma_f32_16x16x32_bf16 v[12:15], v[142:145], v[198:201], v[12:15]
	v_mfma_f32_16x16x32_bf16 v[48:51], v[202:205], v[146:149], v[48:51]
	v_mfma_f32_16x16x32_bf16 v[40:43], v[234:237], v[146:149], v[40:43]
	v_mfma_f32_16x16x32_bf16 v[32:35], v[202:205], v[154:157], v[32:35]
	v_mfma_f32_16x16x32_bf16 v[24:27], v[234:237], v[154:157], v[24:27]
	v_mfma_f32_16x16x32_bf16 v[16:19], v[202:205], v[162:165], v[16:19]
	v_mfma_f32_16x16x32_bf16 v[8:11], v[234:237], v[162:165], v[8:11]
	v_mfma_f32_16x16x32_bf16 v[4:7], v[202:205], v[194:197], v[4:7]
	v_mfma_f32_16x16x32_bf16 v[0:3], v[234:237], v[194:197], v[0:3]
	v_mfma_f32_16x16x32_bf16 v[48:51], v[230:233], v[150:153], v[48:51]
	v_mfma_f32_16x16x32_bf16 v[40:43], v[238:241], v[150:153], v[40:43]
	v_mfma_f32_16x16x32_bf16 v[32:35], v[230:233], v[158:161], v[32:35]
	v_mfma_f32_16x16x32_bf16 v[24:27], v[238:241], v[158:161], v[24:27]
	v_mfma_f32_16x16x32_bf16 v[16:19], v[230:233], v[190:193], v[16:19]
	v_mfma_f32_16x16x32_bf16 v[8:11], v[238:241], v[190:193], v[8:11]
	v_mfma_f32_16x16x32_bf16 v[4:7], v[230:233], v[198:201], v[4:7]
	v_mfma_f32_16x16x32_bf16 v[0:3], v[238:241], v[198:201], v[0:3]
	s_barrier
	s_add_u32 s44, s44, s74
	s_addc_u32 s45, s45, 0
	s_mov_b32 m0, s55
	v_lshl_add_u64 v[250:251], s[44:45], 0, v[174:175]
	ds_read_b128 v[146:149], v228 offset:32768
	ds_read_b128 v[150:153], v228 offset:33792
	ds_read_b128 v[154:157], v228 offset:34816
	ds_read_b128 v[158:161], v228 offset:35840
	ds_read_b128 v[162:165], v228 offset:36864
	ds_read_b128 v[190:193], v228 offset:37888
	ds_read_b128 v[194:197], v228 offset:38912
	ds_read_b128 v[198:201], v228 offset:39936
	global_load_lds_dwordx4 v[250:251], off
	v_lshl_add_u64 v[250:251], s[44:45], 0, v[176:177]
	s_mov_b32 m0, s3
	v_add_u32_e32 v142, 0x18000, v225
	global_load_lds_dwordx4 v[250:251], off
	ds_read_b128 v[130:133], v142
	ds_read_b128 v[134:137], v142 offset:1024
	ds_read_b128 v[138:141], v142 offset:2048
	ds_read_b128 v[142:145], v142 offset:3072
	v_add_u32_e32 v172, 0x1c000, v225
	ds_read_b128 v[202:205], v172
	ds_read_b128 v[230:233], v172 offset:1024
	ds_read_b128 v[234:237], v172 offset:2048
	ds_read_b128 v[238:241], v172 offset:3072
	s_waitcnt vmcnt(8) lgkmcnt(0)
	s_barrier
	v_mfma_f32_16x16x32_bf16 v[124:127], v[130:133], v[146:149], v[124:127]
	v_mfma_f32_16x16x32_bf16 v[120:123], v[138:141], v[146:149], v[120:123]
	v_mfma_f32_16x16x32_bf16 v[112:115], v[130:133], v[154:157], v[112:115]
	v_mfma_f32_16x16x32_bf16 v[104:107], v[138:141], v[154:157], v[104:107]
	v_mfma_f32_16x16x32_bf16 v[96:99], v[130:133], v[162:165], v[96:99]
	v_mfma_f32_16x16x32_bf16 v[88:91], v[138:141], v[162:165], v[88:91]
	v_mfma_f32_16x16x32_bf16 v[80:83], v[130:133], v[194:197], v[80:83]
	v_mfma_f32_16x16x32_bf16 v[72:75], v[138:141], v[194:197], v[72:75]
	v_mfma_f32_16x16x32_bf16 v[124:127], v[134:137], v[150:153], v[124:127]
	v_mfma_f32_16x16x32_bf16 v[120:123], v[142:145], v[150:153], v[120:123]
	v_mfma_f32_16x16x32_bf16 v[112:115], v[134:137], v[158:161], v[112:115]
	v_mfma_f32_16x16x32_bf16 v[104:107], v[142:145], v[158:161], v[104:107]
	v_mfma_f32_16x16x32_bf16 v[96:99], v[134:137], v[190:193], v[96:99]
	v_mfma_f32_16x16x32_bf16 v[88:91], v[142:145], v[190:193], v[88:91]
	v_mfma_f32_16x16x32_bf16 v[80:83], v[134:137], v[198:201], v[80:83]
	v_mfma_f32_16x16x32_bf16 v[72:75], v[142:145], v[198:201], v[72:75]
	v_mfma_f32_16x16x32_bf16 v[116:119], v[202:205], v[146:149], v[116:119]
	v_mfma_f32_16x16x32_bf16 v[108:111], v[234:237], v[146:149], v[108:111]
	v_mfma_f32_16x16x32_bf16 v[100:103], v[202:205], v[154:157], v[100:103]
	v_mfma_f32_16x16x32_bf16 v[92:95], v[234:237], v[154:157], v[92:95]
	v_mfma_f32_16x16x32_bf16 v[84:87], v[202:205], v[162:165], v[84:87]
	v_mfma_f32_16x16x32_bf16 v[76:79], v[234:237], v[162:165], v[76:79]
	v_mfma_f32_16x16x32_bf16 v[68:71], v[202:205], v[194:197], v[68:71]
	v_mfma_f32_16x16x32_bf16 v[64:67], v[234:237], v[194:197], v[64:67]
	v_mfma_f32_16x16x32_bf16 v[116:119], v[230:233], v[150:153], v[116:119]
	v_mfma_f32_16x16x32_bf16 v[108:111], v[238:241], v[150:153], v[108:111]
	v_mfma_f32_16x16x32_bf16 v[100:103], v[230:233], v[158:161], v[100:103]
	v_mfma_f32_16x16x32_bf16 v[92:95], v[238:241], v[158:161], v[92:95]
	v_mfma_f32_16x16x32_bf16 v[84:87], v[230:233], v[190:193], v[84:87]
	v_mfma_f32_16x16x32_bf16 v[76:79], v[238:241], v[190:193], v[76:79]
	v_mfma_f32_16x16x32_bf16 v[68:71], v[230:233], v[198:201], v[68:71]
	v_mfma_f32_16x16x32_bf16 v[64:67], v[238:241], v[198:201], v[64:67]
	s_barrier
; #define PG8_STAGE(bufoff, gbase, voff) do { _Pragma("unroll") for (int _i = 0; _i < 2; ++_i) \
;         __builtin_amdgcn_global_load_lds((const unsigned*)((const char*)(gbase) + (voff)[_i]), (LAS unsigned*)(lds + (bufoff) + ldsw + _i * 8192), 16, 0, 0); } while (0)
; #define PG8_LDA(dst, b, h) do { _Pragma("unroll") for (int m = 0; m < 4; ++m) _Pragma("unroll") for (int k = 0; k < 2; ++k) dst[m][k] = *(const LAS bf16x8*)(lds + PG8_SA(b, h) + aoff + m * 2048 + k * 1024); } while (0)
; #define PG8_MMA(ai, bj, At, Bt) do { __builtin_amdgcn_s_setprio(1); _Pragma("unroll") for (int m = 0; m < 4; ++m) _Pragma("unroll") for (int n = 0; n < 2; ++n) _Pragma("unroll") for (int k = 0; k < 2; ++k) \
;         acc[ai][bj][m][n] = __builtin_amdgcn_mfma_f32_16x16x32_bf16(Bt[n][k], At[m][k], acc[ai][bj][m][n], 0, 0, 0); __builtin_amdgcn_s_setprio(0); } while (0)
; #define PG8_WAIT_V(n) asm volatile("s_waitcnt vmcnt(" #n ")" ::: "memory")
; #define PG8_WAIT_L(n) asm volatile("s_waitcnt lgkmcnt(" #n ")" ::: "memory")
; #define PG8_BAR __builtin_amdgcn_s_barrier()
; #define PG8_SCHED __builtin_amdgcn_sched_barrier(0)
; template <class Epi>
; __device__ __forceinline__ void gemm_phase(LAS unsigned char* lds, const Gemm g, const StaticOrder& S, const Epi& E) {
;     ...
;             PG8_LDA(At, 1, 1); PG8_STAGE(PG8_SA(1, 0), a3, voffA);
;             PG8_BAR; PG8_WAIT_L(0); PG8_MMA(1, 0, At, B0); PG8_BAR; PG8_SCHED;
;             PG8_STAGE(PG8_SB(1, 1), b3 + hstepB, voffB);
;             PG8_WAIT_V(6); PG8_BAR; PG8_MMA(1, 1, At, B1); PG8_BAR;
;     __device__ __forceinline__ void operator()(const f32x4 (&acc)[2][2][4][2], const Unit& u, int wr, int wc, int fr, int fq, const LAS float* rsl) const {
;     ...
;                 const int row = row0 + ai * 128 + m * 16;
;                 const float rstd = rsqrtf(rs[ai][m] * (1.f / 1024.f) + EPS);
;                 bf16_t* rp = proj + (size_t)row * PW + wc * 32 + 8 * fq;
;                 if (pn < 9) {
; #pragma unroll
;                     for (int bj = 0; bj < 2; ++bj) store8bf_nt(rp + pn * 256 + bj * 128, acc[ai][bj][m][0] * rstd, acc[ai][bj][m][1] * rstd);
	ds_read_b128 v[146:149], v228 offset:49152
	ds_read_b128 v[150:153], v228 offset:50176
	ds_read_b128 v[154:157], v228 offset:51200
	ds_read_b128 v[158:161], v228 offset:52224
	ds_read_b128 v[162:165], v228 offset:53248
	ds_read_b128 v[190:193], v228 offset:54272
	ds_read_b128 v[194:197], v228 offset:55296
	ds_read_b128 v[198:201], v228 offset:56320
	s_add_i32 s44, s57, 0x18000
	v_lshl_add_u64 v[166:167], v[166:167], 0, s[88:89]
	s_mov_b32 m0, s44
	v_lshl_add_u64 v[206:207], v[206:207], 0, s[88:89]
	global_load_lds_dwordx4 v[166:167], off
	s_add_i32 m0, s44, 0x2000
	v_lshl_add_u64 v[242:243], v[242:243], 0, s[88:89]
	global_load_lds_dwordx4 v[206:207], off
	s_mov_b32 m0, s60
	v_lshl_add_u64 v[244:245], v[244:245], 0, s[88:89]
	global_load_lds_dwordx4 v[242:243], off
	s_mov_b32 m0, s61
	s_add_i32 s44, s57, 0x1c000
	v_lshl_add_u64 v[246:247], v[246:247], 0, s[88:89]
	global_load_lds_dwordx4 v[244:245], off
	s_mov_b32 m0, s44
	v_lshl_add_u64 v[248:249], v[248:249], 0, s[88:89]
	global_load_lds_dwordx4 v[246:247], off
	s_add_i32 m0, s44, 0x2000
	s_nop 0
	global_load_lds_dwordx4 v[248:249], off
	s_cmp_lt_u32 s35, s16
	s_cbranch_scc1 .Le0_skip
	s_cmp_eq_u32 s32, 0
	s_cbranch_scc1 .Le0_skip
	v_lshl_add_u32 v172, s20, 2, v226
	ds_read2_b32 v[250:251], v172 offset1:16
	ds_read2_b32 v[252:253], v172 offset0:32 offset1:48
	v_add_u32_e32 v242, s34, v171
	v_mad_i64_i32 v[244:245], s[44:45], v242, s0, v[182:183]
	s_lshl_b32 s46, s48, 9
	s_mov_b32 s47, 0
	v_lshl_add_u64 v[244:245], v[244:245], 0, s[46:47]
	s_waitcnt lgkmcnt(0)
	v_fmamk_f32 v246, v250, 0x3a800000, v209
	v_mul_f32_e32 v247, 0x4b800000, v246
	v_cmp_gt_f32_e32 vcc, s81, v246
	s_nop 1
	v_cndmask_b32_e32 v246, v246, v247, vcc
	v_rsq_f32_e32 v246, v246
	s_nop 0
	v_mul_f32_e32 v247, 0x45800000, v246
	v_cndmask_b32_e32 v246, v246, v247, vcc
	v_pk_mul_f32 v[124:125], v[124:125], v[246:247] op_sel_hi:[1,0]
	v_pk_mul_f32 v[126:127], v[126:127], v[246:247] op_sel_hi:[1,0]
	v_pk_mul_f32 v[120:121], v[120:121], v[246:247] op_sel_hi:[1,0]
	v_pk_mul_f32 v[122:123], v[122:123], v[246:247] op_sel_hi:[1,0]
	v_cvt_pk_bf16_f32 v124, v124, v125
	v_cvt_pk_bf16_f32 v125, v126, v127
	v_cvt_pk_bf16_f32 v126, v120, v121
	v_cvt_pk_bf16_f32 v127, v122, v123
	global_store_dwordx4 v[244:245], v[124:127], off nt
	v_pk_mul_f32 v[116:117], v[116:117], v[246:247] op_sel_hi:[1,0]
	v_pk_mul_f32 v[118:119], v[118:119], v[246:247] op_sel_hi:[1,0]
	v_pk_mul_f32 v[108:109], v[108:109], v[246:247] op_sel_hi:[1,0]
	v_pk_mul_f32 v[110:111], v[110:111], v[246:247] op_sel_hi:[1,0]
	v_cvt_pk_bf16_f32 v116, v116, v117
	v_cvt_pk_bf16_f32 v117, v118, v119
	v_cvt_pk_bf16_f32 v118, v108, v109
	v_cvt_pk_bf16_f32 v119, v110, v111
	global_store_dwordx4 v[244:245], v[116:119], off offset:256 nt
	v_add_co_u32_e32 v244, vcc, 0x22000, v244
	s_nop 1
	v_addc_co_u32_e32 v245, vcc, 0, v245, vcc
	v_fmamk_f32 v246, v251, 0x3a800000, v209
	v_mul_f32_e32 v247, 0x4b800000, v246
	v_cmp_gt_f32_e32 vcc, s81, v246
	s_nop 1
	v_cndmask_b32_e32 v246, v246, v247, vcc
	v_rsq_f32_e32 v246, v246
	s_nop 0
	v_mul_f32_e32 v247, 0x45800000, v246
	v_cndmask_b32_e32 v246, v246, v247, vcc
	v_pk_mul_f32 v[112:113], v[112:113], v[246:247] op_sel_hi:[1,0]
	v_pk_mul_f32 v[114:115], v[114:115], v[246:247] op_sel_hi:[1,0]
	v_pk_mul_f32 v[104:105], v[104:105], v[246:247] op_sel_hi:[1,0]
	v_pk_mul_f32 v[106:107], v[106:107], v[246:247] op_sel_hi:[1,0]
	v_cvt_pk_bf16_f32 v112, v112, v113
	v_cvt_pk_bf16_f32 v113, v114, v115
	v_cvt_pk_bf16_f32 v114, v104, v105
	v_cvt_pk_bf16_f32 v115, v106, v107
	global_store_dwordx4 v[244:245], v[112:115], off nt
	v_pk_mul_f32 v[100:101], v[100:101], v[246:247] op_sel_hi:[1,0]
	v_pk_mul_f32 v[102:103], v[102:103], v[246:247] op_sel_hi:[1,0]
	v_pk_mul_f32 v[92:93], v[92:93], v[246:247] op_sel_hi:[1,0]
	v_pk_mul_f32 v[94:95], v[94:95], v[246:247] op_sel_hi:[1,0]
	v_cvt_pk_bf16_f32 v100, v100, v101
	v_cvt_pk_bf16_f32 v101, v102, v103
	v_cvt_pk_bf16_f32 v102, v92, v93
	v_cvt_pk_bf16_f32 v103, v94, v95
	global_store_dwordx4 v[244:245], v[100:103], off offset:256 nt
	v_add_co_u32_e32 v244, vcc, 0x22000, v244
	s_nop 1
	v_addc_co_u32_e32 v245, vcc, 0, v245, vcc
	v_fmamk_f32 v246, v252, 0x3a800000, v209
	v_mul_f32_e32 v247, 0x4b800000, v246
	v_cmp_gt_f32_e32 vcc, s81, v246
	s_nop 1
	v_cndmask_b32_e32 v246, v246, v247, vcc
	v_rsq_f32_e32 v246, v246
	s_nop 0
	v_mul_f32_e32 v247, 0x45800000, v246
	v_cndmask_b32_e32 v246, v246, v247, vcc
	v_pk_mul_f32 v[96:97], v[96:97], v[246:247] op_sel_hi:[1,0]
	v_pk_mul_f32 v[98:99], v[98:99], v[246:247] op_sel_hi:[1,0]
	v_pk_mul_f32 v[88:89], v[88:89], v[246:247] op_sel_hi:[1,0]
	v_pk_mul_f32 v[90:91], v[90:91], v[246:247] op_sel_hi:[1,0]
	v_cvt_pk_bf16_f32 v96, v96, v97
	v_cvt_pk_bf16_f32 v97, v98, v99
	v_cvt_pk_bf16_f32 v98, v88, v89
	v_cvt_pk_bf16_f32 v99, v90, v91
	global_store_dwordx4 v[244:245], v[96:99], off nt
	v_pk_mul_f32 v[84:85], v[84:85], v[246:247] op_sel_hi:[1,0]
	v_pk_mul_f32 v[86:87], v[86:87], v[246:247] op_sel_hi:[1,0]
	v_pk_mul_f32 v[76:77], v[76:77], v[246:247] op_sel_hi:[1,0]
	v_pk_mul_f32 v[78:79], v[78:79], v[246:247] op_sel_hi:[1,0]
	v_cvt_pk_bf16_f32 v84, v84, v85
	v_cvt_pk_bf16_f32 v85, v86, v87
	v_cvt_pk_bf16_f32 v86, v76, v77
	v_cvt_pk_bf16_f32 v87, v78, v79
	global_store_dwordx4 v[244:245], v[84:87], off offset:256 nt
	v_add_co_u32_e32 v244, vcc, 0x22000, v244
	s_nop 1
	v_addc_co_u32_e32 v245, vcc, 0, v245, vcc
	v_fmamk_f32 v246, v253, 0x3a800000, v209
	v_mul_f32_e32 v247, 0x4b800000, v246
	v_cmp_gt_f32_e32 vcc, s81, v246
	s_nop 1
	v_cndmask_b32_e32 v246, v246, v247, vcc
	v_rsq_f32_e32 v246, v246
	s_nop 0
	v_mul_f32_e32 v247, 0x45800000, v246
	v_cndmask_b32_e32 v246, v246, v247, vcc
	v_pk_mul_f32 v[80:81], v[80:81], v[246:247] op_sel_hi:[1,0]
	v_pk_mul_f32 v[82:83], v[82:83], v[246:247] op_sel_hi:[1,0]
	v_pk_mul_f32 v[72:73], v[72:73], v[246:247] op_sel_hi:[1,0]
	v_pk_mul_f32 v[74:75], v[74:75], v[246:247] op_sel_hi:[1,0]
	v_cvt_pk_bf16_f32 v80, v80, v81
	v_cvt_pk_bf16_f32 v81, v82, v83
	v_cvt_pk_bf16_f32 v82, v72, v73
	v_cvt_pk_bf16_f32 v83, v74, v75
	global_store_dwordx4 v[244:245], v[80:83], off nt
	v_pk_mul_f32 v[68:69], v[68:69], v[246:247] op_sel_hi:[1,0]
	v_pk_mul_f32 v[70:71], v[70:71], v[246:247] op_sel_hi:[1,0]
	v_pk_mul_f32 v[64:65], v[64:65], v[246:247] op_sel_hi:[1,0]
	v_pk_mul_f32 v[66:67], v[66:67], v[246:247] op_sel_hi:[1,0]
	v_cvt_pk_bf16_f32 v68, v68, v69
	v_cvt_pk_bf16_f32 v69, v70, v71
	v_cvt_pk_bf16_f32 v70, v64, v65
	v_cvt_pk_bf16_f32 v71, v66, v67
	global_store_dwordx4 v[244:245], v[68:71], off offset:256 nt
	s_waitcnt vmcnt(16) lgkmcnt(0)
	s_barrier
	s_branch .Le0_join
